# scan pass 1 S1c: 16-bit scatter stores of the transposed images issued in a per-lane rotated element order (LDS bank conflicts 8-way -> 2-way)
# speedup vs baseline: 1.0062x; 1.0060x over previous
; __device__ __forceinline__ void scan_pass1(const ScanP& sp, int b, int h, int seg, LAS unsigned char* lds) {
;     ...
;             f32x4 ein, eex, einv;
; #pragma unroll
;             for (int e = 0; e < 4; ++e) { ein[e] = ex2(cl[e]); eex[e] = ex2(cl[e] - lw[e]); einv[e] = __builtin_amdgcn_rcpf(ein[e]); }
;             const f32x4 kkt = kkn * eex, rt = r4 * ein, kh = kp * einv, bh = bb * einv;
;             u32x2 o;
;             o.x = pk2(kkt[0], kkt[1]); o.y = pk2(kkt[2], kkt[3]); *(LAS u32x2*)(lds + O_KK + (tt * 72 + j4) * 2) = o;
;             o.x = pk2(rt[0], rt[1]); o.y = pk2(rt[2], rt[3]); *(LAS u32x2*)(lds + O_R + (tt * 72 + j4) * 2) = o;
;             o.x = pk2(kh[0], kh[1]); o.y = pk2(kh[2], kh[3]); *(LAS u32x2*)(lds + O_K + (tt * 72 + j4) * 2) = o;
;             const unsigned k01 = o.x, k23 = o.y;
;             o.x = pk2(bh[0], bh[1]); o.y = pk2(bh[2], bh[3]); *(LAS u32x2*)(lds + O_B + (tt * 72 + j4) * 2) = o;
;             const unsigned nb01 = pk2(-bh[0], -bh[1]), nb23 = pk2(-bh[2], -bh[3]);
;             const unsigned v01 = pk2(v4[0], v4[1]), v23 = pk2(v4[2], v4[3]);
;             LAS unsigned short* kt = (LAS unsigned short*)(lds + O_KT) + j4 * 40 + tt;
;             kt[0] = (unsigned short)(k01 & 0xffffu); kt[40] = (unsigned short)(k01 >> 16); kt[80] = (unsigned short)(k23 & 0xffffu); kt[120] = (unsigned short)(k23 >> 16);
;             LAS unsigned short* bt = (LAS unsigned short*)(lds + O_BT) + j4 * 40 + tt;
;             bt[0] = (unsigned short)(nb01 & 0xffffu); bt[40] = (unsigned short)(nb01 >> 16); bt[80] = (unsigned short)(nb23 & 0xffffu); bt[120] = (unsigned short)(nb23 >> 16);
;             LAS unsigned short* vt = (LAS unsigned short*)(lds + O_VT) + j4 * 40 + tt;
;             vt[0] = (unsigned short)(v01 & 0xffffu); vt[40] = (unsigned short)(v01 >> 16); vt[80] = (unsigned short)(v23 & 0xffffu); vt[120] = (unsigned short)(v23 >> 16);
;             if (tt == 31) *(LAS f32x4*)(gam + j4) = ein;
;         }
;         __syncthreads();
;         if (w < 4) {
; #pragma unroll
;             for (int i = 0; i < 16; ++i) { P1[i] = 0.f; P2[i] = 0.f; }
; #pragma unroll
;             for (int jb = 0; jb < 2; ++jb)
; #pragma unroll
;                 for (int s = 0; s < 2; ++s) {
;                     const bf16x8 hb = pack8(Hacc[jb], s);
;                     const int off = (ln * 72 + 32 * jb + 16 * s + 4 * hh) * 2;
.LBB0_266:
	s_or_b64 exec, exec, s[0:1]
	v_sub_f32_e32 v0, v80, v100
	v_exp_f32_e32 v104, v80
	v_exp_f32_e32 v105, v81
	v_exp_f32_e32 v2, v0
	v_sub_f32_e32 v0, v81, v101
	v_exp_f32_e32 v106, v82
	v_exp_f32_e32 v107, v83
	v_exp_f32_e32 v3, v0
	v_sub_f32_e32 v0, v82, v102
	v_exp_f32_e32 v82, v0
	v_sub_f32_e32 v0, v83, v103
	v_exp_f32_e32 v83, v0
	v_rcp_f32_e32 v80, v104
	v_rcp_f32_e32 v81, v105
	v_rcp_f32_e32 v110, v106
	v_rcp_f32_e32 v111, v107
	v_pk_mul_f32 v[82:83], v[132:133], v[82:83]
	v_pk_mul_f32 v[2:3], v[130:131], v[2:3]
	s_waitcnt lgkmcnt(0)
	v_pk_mul_f32 v[78:79], v[78:79], v[106:107]
	v_pk_mul_f32 v[76:77], v[76:77], v[104:105]
	v_pk_mul_f32 v[74:75], v[74:75], v[110:111]
	v_pk_mul_f32 v[72:73], v[72:73], v[80:81]
	v_pk_mul_f32 v[110:111], v[136:137], v[110:111]
	v_pk_mul_f32 v[80:81], v[134:135], v[80:81]
	v_cvt_pk_bf16_f32 v2, v2, v3
	v_cvt_pk_bf16_f32 v3, v82, v83
	v_add_u32_e32 v0, 0, v163
	v_cvt_pk_bf16_f32 v76, v76, v77
	v_cvt_pk_bf16_f32 v77, v78, v79
	ds_write2st64_b64 v0, v[2:3], v[76:77] offset0:64 offset1:73
	v_cvt_pk_bf16_f32 v2, v72, v73
	v_cvt_pk_bf16_f32 v3, v74, v75
	v_cvt_pk_bf16_f32 v72, v80, v81
	v_cvt_pk_bf16_f32 v73, v110, v111
	ds_write2st64_b64 v0, v[2:3], v[72:73] offset0:82 offset1:91
	v_xor_b32_e32 v0, 0x80000000, v81
	v_xor_b32_e32 v72, 0x80000000, v80
	v_cvt_pk_bf16_f32 v0, v72, v0
	v_xor_b32_e32 v72, 0x80000000, v110
	v_xor_b32_e32 v73, 0x80000000, v111
	v_cvt_pk_bf16_f32 v72, v72, v73
	v_cvt_pk_bf16_f32 v68, v68, v69
	v_cvt_pk_bf16_f32 v69, v70, v71
	v_mov_b32_e32 v250, v0
	v_mov_b32_e32 v251, v72
	v_lshlrev_b32_e32 v245, 3, v210
	v_and_b32_e32 v245, 48, v245
	v_mov_b32_e32 v246, v245
	v_mad_u32_u24 v247, v246, 5, v164
	v_lshrrev_b64 v[230:231], v246, v[2:3]
	v_lshrrev_b64 v[232:233], v246, v[250:251]
	v_lshrrev_b64 v[234:235], v246, v[68:69]
	ds_write_b16 v247, v230 offset:51200
	ds_write_b16 v247, v232 offset:56320
	ds_write_b16 v247, v234 offset:61440
	v_add_u32_e32 v246, 16, v245
	v_and_b32_e32 v246, 48, v246
	v_mad_u32_u24 v247, v246, 5, v164
	v_lshrrev_b64 v[230:231], v246, v[2:3]
	v_lshrrev_b64 v[232:233], v246, v[250:251]
	v_lshrrev_b64 v[234:235], v246, v[68:69]
	ds_write_b16 v247, v230 offset:51200
	ds_write_b16 v247, v232 offset:56320
	ds_write_b16 v247, v234 offset:61440
	v_add_u32_e32 v246, 32, v245
	v_and_b32_e32 v246, 48, v246
	v_mad_u32_u24 v247, v246, 5, v164
	v_lshrrev_b64 v[230:231], v246, v[2:3]
	v_lshrrev_b64 v[232:233], v246, v[250:251]
	v_lshrrev_b64 v[234:235], v246, v[68:69]
	ds_write_b16 v247, v230 offset:51200
	ds_write_b16 v247, v232 offset:56320
	ds_write_b16 v247, v234 offset:61440
	v_add_u32_e32 v246, 48, v245
	v_and_b32_e32 v246, 48, v246
	v_mad_u32_u24 v247, v246, 5, v164
	v_lshrrev_b64 v[230:231], v246, v[2:3]
	v_lshrrev_b64 v[232:233], v246, v[250:251]
	v_lshrrev_b64 v[234:235], v246, v[68:69]
	ds_write_b16 v247, v230 offset:51200
	ds_write_b16 v247, v232 offset:56320
	ds_write_b16 v247, v234 offset:61440
	s_and_saveexec_b64 s[0:1], s[52:53]
	ds_write_b128 v165, v[104:107]
	s_or_b64 exec, exec, s[0:1]
	v_mul_u32_u24_e32 v0, 0x90, v189
	s_andn2_b64 vcc, exec, s[56:57]
	s_mov_b64 s[0:1], -1
	s_waitcnt lgkmcnt(0)
	s_barrier
	s_cbranch_vccnz .LBB0_284
	v_lshl_add_u32 v2, v188, 4, v0
	v_add_u32_e32 v3, s65, v2
	v_add_u32_e32 v2, s77, v2
	ds_read_b128 v[68:71], v3
	ds_read_b128 v[72:75], v2
	ds_read_b128 v[104:107], v3 offset:32
	ds_read_b128 v[110:113], v2 offset:32
	ds_read_b128 v[230:233], v3 offset:64
	ds_read_b128 v[234:237], v2 offset:64
	ds_read_b128 v[238:241], v3 offset:96
	ds_read_b128 v[242:245], v2 offset:96
	s_mov_b64 s[78:79], -1
	s_and_b64 vcc, exec, s[72:73]
	s_waitcnt lgkmcnt(6)
	v_mfma_f32_32x32x16_bf16 v[68:83], v[68:71], v[72:75], 0
	s_waitcnt lgkmcnt(4)
	v_mfma_f32_32x32x16_bf16 v[68:83], v[104:107], v[110:113], v[68:83]
	s_waitcnt lgkmcnt(2)
	v_mfma_f32_32x32x16_bf16 v[68:83], v[230:233], v[234:237], v[68:83]
	v_lshlrev_b32_e32 v2, 2, v188
	v_or_b32_e32 v117, 2, v2
	v_or_b32_e32 v116, 3, v2
	v_add_u32_e32 v115, 8, v2
	v_add_u32_e32 v109, 10, v2
	v_add_u32_e32 v3, 11, v2
	s_waitcnt lgkmcnt(0)
	v_mfma_f32_32x32x16_bf16 v[68:83], v[238:241], v[242:245], v[68:83]
	v_add_u32_e32 v113, 9, v2
	v_add_u32_e32 v111, 16, v2
	v_add_u32_e32 v106, 17, v2
	v_add_u32_e32 v110, 18, v2
	v_add_u32_e32 v104, 19, v2
	v_add_u32_e32 v114, 24, v2
	v_add_u32_e32 v112, 25, v2
	v_add_u32_e32 v107, 26, v2
	v_add_u32_e32 v105, 27, v2
	v_cmp_lt_i32_e64 s[40:41], v2, v189
	v_cmp_lt_i32_e64 s[50:51], v117, v189
	v_cmp_lt_i32_e64 s[48:49], v116, v189
	v_cmp_lt_i32_e64 s[46:47], v115, v189
	v_cmp_lt_i32_e64 s[44:45], v113, v189
	v_cmp_lt_i32_e64 s[42:43], v109, v189
	v_cmp_lt_i32_e64 s[38:39], v3, v189
	v_cmp_lt_i32_e64 s[36:37], v111, v189
	v_cmp_lt_i32_e64 s[34:35], v106, v189
	v_cmp_lt_i32_e64 s[30:31], v110, v189
	v_cmp_lt_i32_e64 s[28:29], v104, v189
	v_cmp_lt_i32_e64 s[26:27], v114, v189
	v_cmp_lt_i32_e64 s[24:25], v112, v189
	v_cmp_lt_i32_e64 s[22:23], v107, v189
	v_cmp_lt_i32_e64 s[0:1], v105, v189
	s_cbranch_vccz .LBB0_271
; #define LAS __attribute__((address_space(3)))
; __device__ __forceinline__ unsigned pk2(float lo, float hi) { f32x2 v = {lo, hi}; bf16x2_t b = __builtin_convertvector(v, bf16x2_t); return __builtin_bit_cast(unsigned, b); }
; __device__ __forceinline__ void scan_pass1(const ScanP& sp, int b, int h, int seg, LAS unsigned char* lds) {
;     ...
;                 const int oo = (job == 0) ? O_MK : (job == 2) ? O_NK : O_NB;
; #pragma unroll
;                 for (int g = 0; g < 4; ++g) {
;                     float z[4];
; #pragma unroll
;                     for (int e = 0; e < 4; ++e) {
;                         const int s = 8 * g + 4 * hh + e;
;                         const bool keep = (job == 0) ? (s < ln) : (s <= ln);
;                         float v = keep ? Z[4 * g + e] : 0.f; if (job == 3) v = -v; z[e] = v;
;                     }
;                     u32x2 o; o.x = pk2(z[0], z[1]); o.y = pk2(z[2], z[3]);
;                     *(LAS u32x2*)(lds + oo + (ln * 40 + 8 * g + 4 * hh) * 2) = o;
;                 }
	v_lshlrev_b32_e32 v118, 3, v188
	v_mul_u32_u24_e32 v119, 0x50, v189
	v_cmp_le_i32_e32 vcc, v2, v189
	v_add3_u32 v121, s33, v118, v119
	v_cndmask_b32_e64 v118, 0, 1, s[40:41]
	v_cndmask_b32_e64 v119, 0, 1, vcc
	v_cndmask_b32_e64 v118, v119, v118, s[4:5]
	v_and_b32_e32 v118, 1, v118
	v_cmp_eq_u32_e32 vcc, 1, v118
	v_or_b32_e32 v119, v2, v166
	v_cndmask_b32_e64 v123, 0, 1, s[50:51]
	v_cndmask_b32_e32 v118, 0, v68, vcc
	v_cmp_gt_i32_e32 vcc, v189, v119
	v_cndmask_b32_e64 v118, v118, -v118, s[74:75]
	s_mov_b64 s[78:79], 0
	v_cndmask_b32_e32 v119, 0, v69, vcc
	v_cmp_le_i32_e32 vcc, v117, v189
	v_cndmask_b32_e64 v119, v119, -v119, s[74:75]
	v_cvt_pk_bf16_f32 v118, v118, v119
	v_cndmask_b32_e64 v150, 0, 1, vcc
	v_cndmask_b32_e64 v123, v150, v123, s[4:5]
	v_and_b32_e32 v123, 1, v123
	v_cmp_eq_u32_e32 vcc, 1, v123
	v_cndmask_b32_e64 v150, 0, 1, s[48:49]
	s_nop 0
	v_cndmask_b32_e32 v123, 0, v70, vcc
	v_cmp_le_i32_e32 vcc, v116, v189
	v_cndmask_b32_e64 v123, v123, -v123, s[74:75]
	s_nop 0
	v_cndmask_b32_e64 v151, 0, 1, vcc
	v_cndmask_b32_e64 v150, v151, v150, s[4:5]
	v_and_b32_e32 v150, 1, v150
	v_cmp_eq_u32_e32 vcc, 1, v150
	s_nop 1
	v_cndmask_b32_e32 v150, 0, v71, vcc
	v_cndmask_b32_e64 v150, v150, -v150, s[74:75]
	v_cmp_le_i32_e32 vcc, v115, v189
	v_cvt_pk_bf16_f32 v119, v123, v150
	v_cndmask_b32_e64 v123, 0, 1, s[46:47]
	v_cndmask_b32_e64 v150, 0, 1, vcc
	v_cndmask_b32_e64 v123, v150, v123, s[4:5]
	v_and_b32_e32 v123, 1, v123
	v_cmp_eq_u32_e32 vcc, 1, v123
	v_cndmask_b32_e64 v150, 0, 1, s[44:45]
	s_nop 0
	v_cndmask_b32_e32 v123, 0, v72, vcc
	v_cmp_le_i32_e32 vcc, v113, v189
	v_cndmask_b32_e64 v123, v123, -v123, s[74:75]
	s_nop 0
	v_cndmask_b32_e64 v151, 0, 1, vcc
	v_cndmask_b32_e64 v150, v151, v150, s[4:5]
	v_and_b32_e32 v150, 1, v150
	v_cmp_eq_u32_e32 vcc, 1, v150
	v_cndmask_b32_e64 v151, 0, 1, s[42:43]
	s_nop 0
	v_cndmask_b32_e32 v150, 0, v73, vcc
	v_cmp_le_i32_e32 vcc, v109, v189
	v_cndmask_b32_e64 v150, v150, -v150, s[74:75]
	v_cvt_pk_bf16_f32 v150, v123, v150
	v_cndmask_b32_e64 v152, 0, 1, vcc
	v_cndmask_b32_e64 v151, v152, v151, s[4:5]
	v_and_b32_e32 v151, 1, v151
	v_cmp_eq_u32_e32 vcc, 1, v151
	v_cndmask_b32_e64 v152, 0, 1, s[38:39]
	s_nop 0
	v_cndmask_b32_e32 v151, 0, v74, vcc
	v_cmp_le_i32_e32 vcc, v3, v189
	v_cndmask_b32_e64 v151, v151, -v151, s[74:75]
	s_nop 0
	v_cndmask_b32_e64 v153, 0, 1, vcc
	v_cndmask_b32_e64 v152, v153, v152, s[4:5]
	v_and_b32_e32 v152, 1, v152
	v_cmp_eq_u32_e32 vcc, 1, v152
	s_nop 1
	v_cndmask_b32_e32 v152, 0, v75, vcc
	v_cndmask_b32_e64 v152, v152, -v152, s[74:75]
	v_cvt_pk_bf16_f32 v151, v151, v152
	v_cmp_le_i32_e32 vcc, v111, v189
	ds_write2_b64 v121, v[118:119], v[150:151] offset1:2
	v_cndmask_b32_e64 v118, 0, 1, s[36:37]
	v_cndmask_b32_e64 v119, 0, 1, vcc
	v_cndmask_b32_e64 v118, v119, v118, s[4:5]
	v_and_b32_e32 v118, 1, v118
	v_cmp_eq_u32_e32 vcc, 1, v118
	v_cndmask_b32_e64 v119, 0, 1, s[34:35]
	s_nop 0
	v_cndmask_b32_e32 v118, 0, v76, vcc
	v_cmp_le_i32_e32 vcc, v106, v189
	v_cndmask_b32_e64 v118, v118, -v118, s[74:75]
	s_nop 0
	v_cndmask_b32_e64 v123, 0, 1, vcc
	v_cndmask_b32_e64 v119, v123, v119, s[4:5]
	v_and_b32_e32 v119, 1, v119
	v_cmp_eq_u32_e32 vcc, 1, v119
	v_cndmask_b32_e64 v123, 0, 1, s[30:31]
	s_nop 0
	v_cndmask_b32_e32 v119, 0, v77, vcc
	v_cmp_le_i32_e32 vcc, v110, v189
	v_cndmask_b32_e64 v119, v119, -v119, s[74:75]
	v_cvt_pk_bf16_f32 v118, v118, v119
	v_cndmask_b32_e64 v150, 0, 1, vcc
	v_cndmask_b32_e64 v123, v150, v123, s[4:5]
	v_and_b32_e32 v123, 1, v123
	v_cmp_eq_u32_e32 vcc, 1, v123
	v_cndmask_b32_e64 v150, 0, 1, s[28:29]
	s_nop 0
	v_cndmask_b32_e32 v123, 0, v78, vcc
	v_cmp_le_i32_e32 vcc, v104, v189
	v_cndmask_b32_e64 v123, v123, -v123, s[74:75]
	s_nop 0
	v_cndmask_b32_e64 v151, 0, 1, vcc
	v_cndmask_b32_e64 v150, v151, v150, s[4:5]
	v_and_b32_e32 v150, 1, v150
	v_cmp_eq_u32_e32 vcc, 1, v150
	s_nop 1
	v_cndmask_b32_e32 v150, 0, v79, vcc
	v_cndmask_b32_e64 v150, v150, -v150, s[74:75]
	v_cmp_le_i32_e32 vcc, v114, v189
	v_cvt_pk_bf16_f32 v119, v123, v150
	v_cndmask_b32_e64 v123, 0, 1, s[26:27]
	v_cndmask_b32_e64 v150, 0, 1, vcc
	v_cndmask_b32_e64 v123, v150, v123, s[4:5]
	v_and_b32_e32 v123, 1, v123
	v_cmp_eq_u32_e32 vcc, 1, v123
	v_cndmask_b32_e64 v150, 0, 1, s[24:25]
	s_nop 0
	v_cndmask_b32_e32 v123, 0, v80, vcc
	v_cmp_le_i32_e32 vcc, v112, v189
	v_cndmask_b32_e64 v123, v123, -v123, s[74:75]
	s_nop 0
	v_cndmask_b32_e64 v151, 0, 1, vcc
	v_cndmask_b32_e64 v150, v151, v150, s[4:5]
	v_and_b32_e32 v150, 1, v150
	v_cmp_eq_u32_e32 vcc, 1, v150
	v_cndmask_b32_e64 v151, 0, 1, s[22:23]
	s_nop 0
	v_cndmask_b32_e32 v150, 0, v81, vcc
	v_cmp_le_i32_e32 vcc, v107, v189
	v_cndmask_b32_e64 v150, v150, -v150, s[74:75]
	v_cvt_pk_bf16_f32 v150, v123, v150
	v_cndmask_b32_e64 v152, 0, 1, vcc
	v_cndmask_b32_e64 v151, v152, v151, s[4:5]
	v_and_b32_e32 v151, 1, v151
	v_cmp_eq_u32_e32 vcc, 1, v151
	v_cndmask_b32_e64 v152, 0, 1, s[0:1]
	s_nop 0
	v_cndmask_b32_e32 v151, 0, v82, vcc
	v_cmp_le_i32_e32 vcc, v105, v189
	v_cndmask_b32_e64 v151, v151, -v151, s[74:75]
	s_nop 0
	v_cndmask_b32_e64 v153, 0, 1, vcc
	v_cndmask_b32_e64 v152, v153, v152, s[4:5]
	v_and_b32_e32 v152, 1, v152
	v_cmp_eq_u32_e32 vcc, 1, v152
	s_nop 1
	v_cndmask_b32_e32 v152, 0, v83, vcc
	v_cndmask_b32_e64 v152, v152, -v152, s[74:75]
	v_cvt_pk_bf16_f32 v151, v151, v152
	ds_write2_b64 v121, v[118:119], v[150:151] offset0:4 offset1:6
